# attention: Q fragments and bias constant resident in registers per map; final RMSNorm loop: gains hoisted, next row prefetched; x-to-bf16 rows: four loads in flight
# speedup vs baseline: 1.0008x; 1.0008x over previous
.LBB0_64:
	s_waitcnt lgkmcnt(0)
	global_load_dwordx4 v[16:19], v[6:7], off offset:-2048
	global_load_dwordx4 v[30:33], v[6:7], off offset:-1024
	global_load_dwordx4 v[34:37], v[6:7], off
	global_load_dwordx4 v[38:41], v[6:7], off offset:1024
	v_lshl_add_u64 v[20:21], s[46:47], 0, v[4:5]
	v_add_co_u32_e32 v20, vcc, 0xe200000, v20
	s_waitcnt vmcnt(3)
	v_cvt_pk_bf16_f32 v22, v16, v17
	v_addc_co_u32_e32 v21, vcc, 0, v21, vcc
	v_cvt_pk_bf16_f32 v23, v18, v19
	global_store_dwordx2 v[20:21], v[22:23], off
	v_lshlrev_b32_e32 v28, 16, v22
	v_and_b32_e32 v22, 0xffff0000, v22
	v_lshlrev_b32_e32 v29, 16, v23
	v_and_b32_e32 v23, 0xffff0000, v23
	v_mul_f32_e32 v22, v22, v22
	v_mul_f32_e32 v23, v23, v23
	v_fmac_f32_e32 v22, v28, v28
	v_fmac_f32_e32 v23, v29, v29
	v_add_f32_e32 v22, v22, v23
	s_waitcnt vmcnt(3)
	v_cvt_pk_bf16_f32 v24, v30, v31
	v_cvt_pk_bf16_f32 v25, v32, v33
	global_store_dwordx2 v[20:21], v[24:25], off offset:512
	v_lshlrev_b32_e32 v23, 16, v24
	v_and_b32_e32 v24, 0xffff0000, v24
	v_lshlrev_b32_e32 v28, 16, v25
	v_and_b32_e32 v25, 0xffff0000, v25
	v_mul_f32_e32 v24, v24, v24
	v_mul_f32_e32 v25, v25, v25
	v_fmac_f32_e32 v24, v23, v23
	v_fmac_f32_e32 v25, v28, v28
	v_add_f32_e32 v23, v24, v25
	v_add_f32_e32 v22, v22, v23
	s_waitcnt vmcnt(3)
	v_cvt_pk_bf16_f32 v26, v34, v35
	v_cvt_pk_bf16_f32 v27, v36, v37
	global_store_dwordx2 v[20:21], v[26:27], off offset:1024
	v_lshlrev_b32_e32 v23, 16, v26
	v_and_b32_e32 v24, 0xffff0000, v26
	v_and_b32_e32 v26, 0xffff0000, v27
	v_lshlrev_b32_e32 v25, 16, v27
	v_mul_f32_e32 v24, v24, v24
	v_mul_f32_e32 v26, v26, v26
	v_fmac_f32_e32 v24, v23, v23
	v_fmac_f32_e32 v26, v25, v25
	v_add_f32_e32 v23, v24, v26
	v_add_f32_e32 v24, v22, v23
	s_waitcnt vmcnt(3)
	v_cvt_pk_bf16_f32 v22, v38, v39
	v_cvt_pk_bf16_f32 v23, v40, v41
	v_and_b32_e32 v17, 0xffff0000, v22
	v_and_b32_e32 v19, 0xffff0000, v23
	v_lshlrev_b32_e32 v16, 16, v22
	v_lshlrev_b32_e32 v18, 16, v23
	v_mul_f32_e32 v17, v17, v17
	v_mul_f32_e32 v19, v19, v19
	v_fmac_f32_e32 v17, v16, v16
	v_fmac_f32_e32 v19, v18, v18
	v_add_f32_e32 v16, v17, v19
	v_add_f32_e32 v16, v24, v16
	ds_bpermute_b32 v17, v8, v16
	global_store_dwordx2 v[20:21], v[22:23], off offset:1536
	s_waitcnt lgkmcnt(0)
	v_add_f32_e32 v16, v16, v17
	ds_bpermute_b32 v17, v9, v16
	s_waitcnt lgkmcnt(0)
	v_add_f32_e32 v16, v16, v17
	ds_bpermute_b32 v17, v10, v16
	s_waitcnt lgkmcnt(0)
	v_add_f32_e32 v16, v16, v17
	ds_bpermute_b32 v17, v11, v16
	s_waitcnt lgkmcnt(0)
	v_add_f32_e32 v16, v16, v17
	ds_bpermute_b32 v17, v12, v16
	s_waitcnt lgkmcnt(0)
	v_add_f32_e32 v16, v16, v17
	ds_bpermute_b32 v17, v13, v16
	s_and_saveexec_b64 s[12:13], s[0:1]
	s_cbranch_execz .LBB0_63
	s_waitcnt lgkmcnt(0)
	v_add_f32_e32 v16, v16, v17
	v_lshl_add_u64 v[18:19], s[46:47], 0, v[2:3]
	v_cndmask_b32_e64 v16, 0, v16, s[4:5]
	global_store_dword v[18:19], v16, off
	s_branch .LBB0_63

.LBB0_511:
	s_bitcmp1_b32 s24, 0
	s_cselect_b64 s[28:29], -1, 0
	s_and_b64 vcc, exec, s[28:29]
	s_cbranch_vccnz .LBB0_514
	s_waitcnt vmcnt(0) lgkmcnt(0)
	s_barrier
	s_cmp_lg_u32 s26, 0
	s_cbranch_scc1 .Latt_q_resident
	ds_read_b128 v[230:233], v209
	ds_read_b128 v[234:237], v209 offset:32
	ds_read_b128 v[242:245], v209 offset:64
	ds_read_b128 v[246:249], v209 offset:96
	v_mov_b32_e32 v238, s18
	ds_read_b32 v238, v238
.Latt_q_resident:
	s_cmp_ge_u32 s24, s59
	s_cbranch_scc1 .LBB0_514
	s_xor_b32 s13, s27, 2
	s_mulk_i32 s13, 0x6000
	v_lshl_add_u64 v[66:67], s[46:47], 0, v[152:153]
	s_mov_b64 s[28:29], 0x1e204000
	s_add_i32 s30, s60, s13
	v_lshl_add_u64 v[68:69], v[66:67], 0, s[28:29]
	s_mov_b32 m0, s30
	s_add_i32 s13, s61, s13
	global_load_lds_dwordx4 v[68:69], off
	v_lshl_add_u64 v[68:69], s[46:47], 0, v[130:131]
	v_lshl_add_u64 v[70:71], v[68:69], 0, s[66:67]
	s_add_i32 m0, s13, 0x2000
	s_mov_b64 s[28:29], 0x1e206000
	global_load_lds_dwordx4 v[70:71], off
	v_lshl_add_u64 v[70:71], s[46:47], 0, v[132:133]
	v_lshl_add_u64 v[72:73], v[70:71], 0, s[66:67]
	s_add_i32 m0, s13, 0x2400
	v_lshl_add_u64 v[66:67], v[66:67], 0, s[28:29]
	global_load_lds_dwordx4 v[72:73], off
	s_add_i32 m0, s30, 0x6000
	s_nop 0
	global_load_lds_dwordx4 v[66:67], off
	v_lshl_add_u64 v[66:67], v[68:69], 0, s[64:65]
	s_add_i32 m0, s13, 0x8000
	s_nop 0
	global_load_lds_dwordx4 v[66:67], off
	v_lshl_add_u64 v[66:67], v[70:71], 0, s[64:65]
	s_add_i32 m0, s13, 0x8400
	s_nop 0
	global_load_lds_dwordx4 v[66:67], off
.LBB0_514:
	s_cmp_gt_i32 s23, s86
	s_cbranch_scc1 .LBB0_510
	s_mul_i32 s13, s27, 0x6000
	s_add_i32 s13, s13, 0
	s_cmpk_gt_i32 s25, 0x70
	s_cselect_b64 vcc, -1, 0
	s_add_i32 s28, s13, 0x2000
	v_add_u32_e32 v156, s28, v205
	v_add_u32_e32 v0, s13, v205
	v_add_u32_e32 v82, s13, v206
	v_add_u32_e32 v83, s13, v207
	v_add_u32_e32 v84, s13, v208
	ds_read_b128 v[174:177], v0
	ds_read_b128 v[178:181], v82
	ds_read_b128 v[182:185], v83
	ds_read_b128 v[186:189], v84
	ds_read_b128 v[190:193], v0 offset:4096
	ds_read_b128 v[194:197], v82 offset:4096
	ds_read_b128 v[198:201], v83 offset:4096
	ds_read_b128 v[220:223], v84 offset:4096
	s_waitcnt lgkmcnt(0)
	v_cndmask_b32_e32 v157, 0, v238, vcc
	v_xor_b32_e32 v0, 32, v156
	v_sub_f32_e32 v66, v157, v154
	ds_read_b128 v[126:129], v156
	ds_read_b128 v[122:125], v156 offset:4096
	ds_read_b128 v[118:121], v156 offset:8192
	ds_read_b128 v[114:117], v156 offset:12288
	ds_read_b128 v[110:113], v0
	ds_read_b128 v[106:109], v0 offset:4096
	ds_read_b128 v[102:105], v0 offset:8192
	ds_read_b128 v[98:101], v0 offset:12288
	v_mov_b32_e32 v67, v66
	v_mov_b32_e32 v68, v66
	v_mov_b32_e32 v69, v66
	v_mov_b32_e32 v70, v66
	v_mov_b32_e32 v71, v66
	v_mov_b32_e32 v72, v66
	v_mov_b32_e32 v73, v66
	v_mov_b32_e32 v74, v66
	v_mov_b32_e32 v75, v66
	v_mov_b32_e32 v76, v66
	v_mov_b32_e32 v77, v66
	v_mov_b32_e32 v78, v66
	v_mov_b32_e32 v79, v66
	v_mov_b32_e32 v80, v66
	v_mov_b32_e32 v81, v66
	s_nop 1
	v_mfma_f32_32x32x16_bf16 v[82:97], v[174:177], v[230:233], v[66:81]
	s_and_b64 vcc, exec, vcc
	v_mfma_f32_32x32x16_bf16 v[66:81], v[190:193], v[230:233], v[66:81]
	v_mfma_f32_32x32x16_bf16 v[82:97], v[178:181], v[234:237], v[82:97]
	v_mfma_f32_32x32x16_bf16 v[66:81], v[194:197], v[234:237], v[66:81]
	v_mfma_f32_32x32x16_bf16 v[82:97], v[182:185], v[242:245], v[82:97]
	v_mfma_f32_32x32x16_bf16 v[66:81], v[198:201], v[242:245], v[66:81]
	v_mfma_f32_32x32x16_bf16 v[82:97], v[186:189], v[246:249], v[82:97]
	v_mfma_f32_32x32x16_bf16 v[66:81], v[220:223], v[246:249], v[66:81]
	s_cbranch_vccnz .LBB0_517
	v_add_u32_e32 v0, s26, v214
	v_add_u32_e32 v157, 0x18094, v0
	ds_read2_b32 v[158:159], v157 offset0:58 offset1:59
	ds_read2_b32 v[160:161], v157 offset0:26 offset1:27
	ds_read2_b32 v[162:163], v157 offset0:56 offset1:57
	ds_read2_b32 v[164:165], v157 offset0:24 offset1:25
	ds_read2_b32 v[166:167], v157 offset0:50 offset1:51
	ds_read2_b32 v[168:169], v157 offset0:18 offset1:19
	ds_read2_b32 v[174:175], v157 offset0:48 offset1:49
	ds_read2_b32 v[176:177], v157 offset0:16 offset1:17
	ds_read2_b32 v[178:179], v157 offset0:42 offset1:43
	ds_read2_b32 v[180:181], v157 offset0:10 offset1:11
	ds_read2_b32 v[182:183], v157 offset0:40 offset1:41
	ds_read2_b32 v[184:185], v157 offset0:8 offset1:9
	ds_read2_b32 v[190:191], v157 offset0:34 offset1:35
	ds_read2_b32 v[192:193], v157 offset0:2 offset1:3
	ds_read2_b32 v[194:195], v157 offset0:32 offset1:33
	ds_read2_b32 v[196:197], v157 offset0:0 offset1:1
	s_waitcnt lgkmcnt(0)
	v_pk_add_f32 v[82:83], v[82:83], v[158:159] op_sel:[0,1] op_sel_hi:[1,0]
	v_pk_add_f32 v[66:67], v[66:67], v[160:161] op_sel:[0,1] op_sel_hi:[1,0]
	v_pk_add_f32 v[84:85], v[84:85], v[162:163] op_sel:[0,1] op_sel_hi:[1,0]
	v_pk_add_f32 v[68:69], v[68:69], v[164:165] op_sel:[0,1] op_sel_hi:[1,0]
	v_pk_add_f32 v[86:87], v[86:87], v[166:167] op_sel:[0,1] op_sel_hi:[1,0]
	v_pk_add_f32 v[70:71], v[70:71], v[168:169] op_sel:[0,1] op_sel_hi:[1,0]
	v_pk_add_f32 v[88:89], v[88:89], v[174:175] op_sel:[0,1] op_sel_hi:[1,0]
	v_pk_add_f32 v[72:73], v[72:73], v[176:177] op_sel:[0,1] op_sel_hi:[1,0]
	v_pk_add_f32 v[90:91], v[90:91], v[178:179] op_sel:[0,1] op_sel_hi:[1,0]
	v_pk_add_f32 v[74:75], v[74:75], v[180:181] op_sel:[0,1] op_sel_hi:[1,0]
	v_pk_add_f32 v[92:93], v[92:93], v[182:183] op_sel:[0,1] op_sel_hi:[1,0]
	v_pk_add_f32 v[76:77], v[76:77], v[184:185] op_sel:[0,1] op_sel_hi:[1,0]
	v_pk_add_f32 v[94:95], v[94:95], v[190:191] op_sel:[0,1] op_sel_hi:[1,0]
	v_pk_add_f32 v[78:79], v[78:79], v[192:193] op_sel:[0,1] op_sel_hi:[1,0]
	v_pk_add_f32 v[96:97], v[96:97], v[194:195] op_sel:[0,1] op_sel_hi:[1,0]
	v_pk_add_f32 v[80:81], v[80:81], v[196:197] op_sel:[0,1] op_sel_hi:[1,0]

.LBB0_1125:
	v_readlane_b32 s0, v252, 56
	s_lshl_b32 s0, s0, 11
	v_readlane_b32 s1, v251, 57
	s_add_i32 s0, s0, s1
	v_readlane_b32 s1, v250, 37
	s_lshl_b32 s1, s1, 3
	v_readlane_b32 s20, v253, 30
	s_add_i32 s2, s0, s1
	v_readlane_b32 s21, v253, 31
	s_and_b64 s[0:1], s[20:21], exec
	v_readlane_b32 s0, v251, 12
	s_cselect_b32 s0, s0, s2
	v_mbcnt_lo_u32_b32 v2, -1, 0
	v_mbcnt_hi_u32_b32 v2, -1, v2
	s_cmpk_gt_i32 s0, 0x3fff
	v_readlane_b32 s1, v251, 13
	s_cbranch_scc1 .LBB0_1128
	s_and_b64 s[2:3], s[20:21], exec
	v_readlane_b32 s2, v250, 58
	v_readlane_b32 s4, v250, 19
	s_cselect_b32 s2, s2, 1
	v_readlane_b32 s5, v250, 20
	v_readlane_b32 s8, v250, 23
	s_ashr_i32 s1, s0, 31
	s_add_i32 s8, s2, s0
	s_lshl_b64 s[4:5], s[0:1], 11
	s_add_u32 s4, s46, s4
	v_ashrrev_i32_e32 v3, 31, v2
	v_lshlrev_b32_e32 v0, 2, v2
	v_readlane_b32 s3, v250, 59
	v_readlane_b32 s12, v250, 27
	v_readlane_b32 s13, v250, 28
	v_readlane_b32 s14, v250, 29
	v_readlane_b32 s15, v250, 30
	v_readlane_b32 s16, v250, 31
	v_readlane_b32 s17, v250, 32
	s_addc_u32 s5, s47, s5
	v_xor_b32_e32 v6, 4, v0
	v_xor_b32_e32 v7, 8, v0
	v_xor_b32_e32 v8, 16, v0
	v_xor_b32_e32 v9, 32, v0
	v_xor_b32_e32 v10, 64, v0
	v_xor_b32_e32 v11, 0x80, v0
	v_lshlrev_b32_e32 v0, 3, v2
	v_readlane_b32 s18, v250, 33
	v_readlane_b32 s19, v250, 34
	s_mov_b64 s[12:13], s[16:17]
	v_lshl_add_u64 v[2:3], v[2:3], 4, s[4:5]
	s_mov_b64 s[4:5], 0x1c200000
	s_ashr_i32 s3, s2, 31
	s_mov_b64 s[14:15], s[18:19]
	v_lshl_add_u64 v[2:3], v[2:3], 0, s[4:5]
	s_lshl_b64 s[4:5], s[2:3], 11
	s_lshl_b64 s[0:1], s[0:1], 12
	v_ashrrev_i32_e32 v1, 31, v0
	s_add_u32 s0, s14, s0
	v_lshlrev_b64 v[4:5], 2, v[0:1]
	v_readlane_b32 s6, v250, 21
	v_readlane_b32 s7, v250, 22
	v_readlane_b32 s9, v250, 24
	s_addc_u32 s1, s15, s1
	v_lshl_add_u64 v[0:1], s[12:13], 0, v[4:5]
	v_lshl_add_u64 v[4:5], s[0:1], 0, v[4:5]
	s_lshl_b64 s[6:7], s[2:3], 12
	s_mov_b32 s9, 0
	v_mov_b32_e32 v12, 0x358637bd
	s_mov_b32 s3, 0xf800000
	v_mov_b32_e32 v13, 0x260
	v_readlane_b32 s10, v250, 25
	v_readlane_b32 s11, v250, 26
	global_load_dwordx4 v[76:79], v[2:3], off
	global_load_dwordx4 v[80:83], v[2:3], off offset:1024
	global_load_dwordx4 v[60:63], v[0:1], off offset:16
	global_load_dwordx4 v[64:67], v[0:1], off
	global_load_dwordx4 v[68:71], v[0:1], off offset:2048
	global_load_dwordx4 v[72:75], v[0:1], off offset:2064
	v_lshl_add_u64 v[2:3], v[2:3], 0, s[4:5]
.LBB0_1127:
	s_add_i32 s10, s9, 1
	s_cmpk_lt_i32 s8, 0x4000
	s_waitcnt vmcnt(4)
	v_lshlrev_b32_e32 v32, 16, v76
	v_and_b32_e32 v33, 0xffff0000, v76
	v_lshlrev_b32_e32 v30, 16, v83
	v_and_b32_e32 v31, 0xffff0000, v83
	v_lshlrev_b32_e32 v14, 16, v77
	v_and_b32_e32 v15, 0xffff0000, v77
	v_lshlrev_b32_e32 v40, 16, v82
	v_and_b32_e32 v41, 0xffff0000, v82
	v_lshlrev_b32_e32 v34, 16, v78
	v_and_b32_e32 v35, 0xffff0000, v78
	v_lshlrev_b32_e32 v16, 16, v79
	v_and_b32_e32 v17, 0xffff0000, v79
	v_lshlrev_b32_e32 v36, 16, v80
	v_and_b32_e32 v37, 0xffff0000, v80
	v_lshlrev_b32_e32 v38, 16, v81
	v_and_b32_e32 v39, 0xffff0000, v81
	global_load_dwordx4 v[76:79], v[2:3], off
	global_load_dwordx4 v[80:83], v[2:3], off offset:1024
	v_lshl_add_u64 v[2:3], v[2:3], 0, s[4:5]
	v_pk_mul_f32 v[20:21], v[32:33], v[32:33]
	v_pk_mul_f32 v[42:43], v[14:15], v[14:15]
	v_add_f32_e32 v20, v20, v21
	v_add_f32_e32 v20, v20, v42
	v_pk_mul_f32 v[44:45], v[34:35], v[34:35]
	v_add_f32_e32 v20, v20, v43
	v_add_f32_e32 v20, v20, v44
	v_pk_mul_f32 v[46:47], v[16:17], v[16:17]
	v_add_f32_e32 v20, v20, v45
	v_add_f32_e32 v20, v20, v46
	v_pk_mul_f32 v[48:49], v[36:37], v[36:37]
	v_add_f32_e32 v20, v20, v47
	v_add_f32_e32 v20, v20, v48
	v_pk_mul_f32 v[50:51], v[38:39], v[38:39]
	v_add_f32_e32 v20, v20, v49
	v_add_f32_e32 v20, v20, v50
	v_pk_mul_f32 v[52:53], v[40:41], v[40:41]
	v_add_f32_e32 v20, v20, v51
	v_add_f32_e32 v20, v20, v52
	v_pk_mul_f32 v[18:19], v[30:31], v[30:31]
	v_add_f32_e32 v20, v20, v53
	v_add_f32_e32 v18, v20, v18
	v_add_f32_e32 v18, v18, v19
	ds_bpermute_b32 v19, v6, v18
	s_waitcnt lgkmcnt(0)
	v_add_f32_e32 v18, v18, v19
	ds_bpermute_b32 v19, v7, v18
	s_waitcnt lgkmcnt(0)
	v_add_f32_e32 v18, v18, v19
	ds_bpermute_b32 v19, v8, v18
	s_waitcnt lgkmcnt(0)
	v_add_f32_e32 v18, v18, v19
	ds_bpermute_b32 v19, v9, v18
	s_waitcnt lgkmcnt(0)
	v_add_f32_e32 v18, v18, v19
	ds_bpermute_b32 v19, v10, v18
	s_waitcnt lgkmcnt(0)
	v_add_f32_e32 v18, v18, v19
	ds_bpermute_b32 v19, v11, v18
	s_waitcnt lgkmcnt(0)
	v_add_f32_e32 v18, v18, v19
	v_fmamk_f32 v18, v18, 0x3a800000, v12
	v_mul_f32_e32 v19, 0x4f800000, v18
	v_cmp_gt_f32_e32 vcc, s3, v18
	s_nop 1
	v_cndmask_b32_e32 v18, v18, v19, vcc
	v_sqrt_f32_e32 v19, v18
	s_nop 0
	v_add_u32_e32 v20, -1, v19
	v_add_u32_e32 v21, 1, v19
	v_fma_f32 v42, -v20, v19, v18
	v_fma_f32 v43, -v21, v19, v18
	v_cmp_ge_f32_e64 s[0:1], 0, v42
	s_nop 1
	v_cndmask_b32_e64 v19, v19, v20, s[0:1]
	v_cmp_lt_f32_e64 s[0:1], 0, v43
	s_nop 1
	v_cndmask_b32_e64 v19, v19, v21, s[0:1]
	v_mul_f32_e32 v20, 0x37800000, v19
	v_cndmask_b32_e32 v19, v19, v20, vcc
	v_cmp_class_f32_e32 vcc, v18, v13
	s_nop 1
	v_cndmask_b32_e32 v18, v19, v18, vcc
	v_div_scale_f32 v19, s[0:1], v18, v18, 1.0
	v_rcp_f32_e32 v21, v19
	v_div_scale_f32 v20, vcc, 1.0, v18, 1.0
	s_cselect_b64 s[0:1], -1, 0
	v_fma_f32 v42, -v19, v21, 1.0
	v_fmac_f32_e32 v21, v42, v21
	v_mul_f32_e32 v42, v20, v21
	v_fma_f32 v43, -v19, v42, v20
	v_fmac_f32_e32 v42, v43, v21
	v_fma_f32 v19, -v19, v42, v20
	v_div_fmas_f32 v19, v19, v21, v42
	v_div_fixup_f32 v42, v19, v18, 1.0
	v_pk_mul_f32 v[18:19], v[42:43], v[32:33] op_sel_hi:[0,1]
	v_pk_mul_f32 v[14:15], v[42:43], v[14:15] op_sel_hi:[0,1]
	v_pk_mul_f32 v[32:33], v[42:43], v[34:35] op_sel_hi:[0,1]
	v_pk_mul_f32 v[20:21], v[42:43], v[16:17] op_sel_hi:[0,1]
	s_waitcnt vmcnt(2)
	v_pk_mul_f32 v[16:17], v[14:15], v[66:67]
	v_pk_mul_f32 v[14:15], v[18:19], v[64:65]
	v_pk_mul_f32 v[20:21], v[20:21], v[62:63]
	v_pk_mul_f32 v[18:19], v[32:33], v[60:61]
	global_store_dwordx4 v[4:5], v[14:17], off
	global_store_dwordx4 v[4:5], v[18:21], off offset:16
	s_cmp_lt_u32 s9, 7
	s_mov_b32 s9, s10
	s_cselect_b64 s[10:11], -1, 0
	s_or_b64 s[10:11], s[20:21], s[10:11]
	v_pk_mul_f32 v[22:23], v[42:43], v[38:39] op_sel_hi:[0,1]
	v_pk_mul_f32 v[24:25], v[42:43], v[36:37] op_sel_hi:[0,1]
	s_and_b64 s[0:1], s[0:1], s[10:11]
	v_pk_mul_f32 v[26:27], v[42:43], v[30:31] op_sel_hi:[0,1]
	v_pk_mul_f32 v[28:29], v[42:43], v[40:41] op_sel_hi:[0,1]
	s_add_i32 s8, s8, s2
	s_andn2_b64 vcc, exec, s[0:1]
	s_nop 0
	v_pk_mul_f32 v[14:15], v[24:25], v[68:69]
	v_pk_mul_f32 v[16:17], v[22:23], v[70:71]
	v_pk_mul_f32 v[18:19], v[28:29], v[72:73]
	v_pk_mul_f32 v[20:21], v[26:27], v[74:75]
	global_store_dwordx4 v[4:5], v[14:17], off offset:2048
	global_store_dwordx4 v[4:5], v[18:21], off offset:2064
	v_lshl_add_u64 v[4:5], v[4:5], 0, s[6:7]
	s_cbranch_vccz .LBB0_1127
